# top-k radix count loop leaves its 33-register sequence early when the row's visible length covers fewer registers (remaining keys are zero)
# speedup vs baseline: 1.0794x; 1.0006x over previous
; DI void topk_select(const float* scores, int* sel, char* smem) {
;     ...
;   for (int row = blockIdx.x * 8 + w; row < M; row += gridDim.x * 8) {
;     const int t = row % T;
;     const int c = t < 16 ? 0 : 1 + ((t - 16) >> 6);
;     const int nvis = 16 + 64 * c;
;     if (nvis <= 256) continue;
;     unsigned u[33];
;     const float* sr = scores + (size_t)row * SROW;
; #pragma unroll
;     for (int j = 0; j < 33; ++j) {
;       const int idx = lane + 64 * j;
;       u[j] = __float_as_uint(sr[idx < nvis ? idx : nvis - 1]);
;     }
; #pragma unroll
;     for (int j = 0; j < 33; ++j) {
;       const int idx = lane + 64 * j;
;       const unsigned bits = u[j];
;       u[j] = idx < nvis ? ((bits & 0x80000000u) ? ~bits : (bits | 0x80000000u)) : 0u;
;     }
.LBB0_581:
	s_mul_hi_i32 s0, s18, 0xfe03f81
	s_lshr_b32 s1, s0, 31
	s_ashr_i32 s0, s0, 7
	s_add_i32 s0, s0, s1
	s_mulk_i32 s0, 0x810
	s_sub_i32 s0, s18, s0
	s_add_i32 s1, s0, -16
	s_andn2_b32 s1, s1, 63
	s_addk_i32 s1, 0x50
	s_cmp_gt_i32 s0, 15
	s_cselect_b32 s4, s1, 16
	s_cmpk_lt_i32 s4, 0x101
	s_cbranch_scc1 .LBB0_580
	s_add_i32 s100, s4, 63
	s_lshr_b32 s100, s100, 6
	s_ashr_i32 s19, s18, 31
	s_mul_i32 s0, s18, 0x2080
	s_mul_hi_i32 s1, s18, 0x2080
	s_add_u32 s0, s24, s0
	s_addc_u32 s1, s25, s1
	s_add_i32 s5, s4, -1
	v_min_i32_e32 v164, s5, v4
	v_lshl_add_u64 v[36:37], v[164:165], 2, s[0:1]
	v_min_i32_e32 v164, s5, v5
	global_load_dword v42, v[36:37], off
	v_lshl_add_u64 v[36:37], v[164:165], 2, s[0:1]
	v_min_i32_e32 v164, s5, v6
	global_load_dword v43, v[36:37], off
	v_lshl_add_u64 v[36:37], v[164:165], 2, s[0:1]
	v_min_i32_e32 v164, s5, v7
	global_load_dword v44, v[36:37], off
	v_lshl_add_u64 v[36:37], v[164:165], 2, s[0:1]
	v_min_i32_e32 v164, s5, v8
	global_load_dword v45, v[36:37], off
	v_lshl_add_u64 v[36:37], v[164:165], 2, s[0:1]
	v_min_i32_e32 v164, s5, v9
	global_load_dword v46, v[36:37], off
	v_lshl_add_u64 v[36:37], v[164:165], 2, s[0:1]
	v_min_i32_e32 v164, s5, v10
	global_load_dword v47, v[36:37], off
	v_lshl_add_u64 v[36:37], v[164:165], 2, s[0:1]
	v_min_i32_e32 v164, s5, v11
	global_load_dword v48, v[36:37], off
	v_lshl_add_u64 v[36:37], v[164:165], 2, s[0:1]
	v_min_i32_e32 v164, s5, v12
	global_load_dword v49, v[36:37], off
	v_lshl_add_u64 v[36:37], v[164:165], 2, s[0:1]
	v_min_i32_e32 v164, s5, v13
	global_load_dword v50, v[36:37], off
	v_lshl_add_u64 v[36:37], v[164:165], 2, s[0:1]
	v_min_i32_e32 v164, s5, v14
	global_load_dword v51, v[36:37], off
	v_lshl_add_u64 v[36:37], v[164:165], 2, s[0:1]
	v_min_i32_e32 v164, s5, v15
	global_load_dword v52, v[36:37], off
	v_lshl_add_u64 v[36:37], v[164:165], 2, s[0:1]
	v_min_i32_e32 v164, s5, v16
	global_load_dword v53, v[36:37], off
	v_lshl_add_u64 v[36:37], v[164:165], 2, s[0:1]
	v_min_i32_e32 v164, s5, v17
	global_load_dword v54, v[36:37], off
	v_lshl_add_u64 v[36:37], v[164:165], 2, s[0:1]
	v_min_i32_e32 v164, s5, v18
	global_load_dword v70, v[36:37], off
	v_lshl_add_u64 v[36:37], v[164:165], 2, s[0:1]
	v_min_i32_e32 v164, s5, v19
	global_load_dword v71, v[36:37], off
	v_lshl_add_u64 v[36:37], v[164:165], 2, s[0:1]
	v_min_i32_e32 v164, s5, v20
	global_load_dword v72, v[36:37], off
	v_lshl_add_u64 v[36:37], v[164:165], 2, s[0:1]
	v_min_i32_e32 v164, s5, v21
	global_load_dword v73, v[36:37], off
	v_lshl_add_u64 v[36:37], v[164:165], 2, s[0:1]
	v_min_i32_e32 v164, s5, v22
	global_load_dword v74, v[36:37], off
	v_lshl_add_u64 v[36:37], v[164:165], 2, s[0:1]
	v_min_i32_e32 v164, s5, v23
	global_load_dword v75, v[36:37], off
	v_lshl_add_u64 v[36:37], v[164:165], 2, s[0:1]
	v_min_i32_e32 v164, s5, v24
	global_load_dword v76, v[36:37], off
	v_lshl_add_u64 v[36:37], v[164:165], 2, s[0:1]
	v_min_i32_e32 v164, s5, v25
	global_load_dword v77, v[36:37], off
	v_lshl_add_u64 v[36:37], v[164:165], 2, s[0:1]
	v_min_i32_e32 v164, s5, v26
	global_load_dword v78, v[36:37], off
	v_lshl_add_u64 v[36:37], v[164:165], 2, s[0:1]
	v_min_i32_e32 v164, s5, v27
	global_load_dword v79, v[36:37], off
	v_lshl_add_u64 v[36:37], v[164:165], 2, s[0:1]
	v_min_i32_e32 v164, s5, v28
	global_load_dword v80, v[36:37], off
	v_lshl_add_u64 v[36:37], v[164:165], 2, s[0:1]
	v_min_i32_e32 v164, s5, v29
	global_load_dword v81, v[36:37], off
	v_lshl_add_u64 v[36:37], v[164:165], 2, s[0:1]
	v_min_i32_e32 v164, s5, v30
	global_load_dword v82, v[36:37], off
	v_lshl_add_u64 v[36:37], v[164:165], 2, s[0:1]
	v_min_i32_e32 v164, s5, v31
	global_load_dword v83, v[36:37], off
	v_lshl_add_u64 v[36:37], v[164:165], 2, s[0:1]
	v_min_i32_e32 v164, s5, v32
	global_load_dword v84, v[36:37], off
	v_lshl_add_u64 v[36:37], v[164:165], 2, s[0:1]
	v_min_i32_e32 v164, s5, v33
	global_load_dword v39, v[36:37], off
	v_lshl_add_u64 v[36:37], v[164:165], 2, s[0:1]
	v_min_i32_e32 v164, s5, v34
	global_load_dword v38, v[36:37], off
	v_lshl_add_u64 v[36:37], v[164:165], 2, s[0:1]
	v_min_i32_e32 v164, s5, v35
	v_lshl_add_u64 v[40:41], v[164:165], 2, s[0:1]
	v_min_i32_e32 v164, s5, v2
	global_load_dword v37, v[36:37], off
	v_sub_u32_e32 v69, s4, v2
	global_load_dword v36, v[40:41], off
	v_lshl_add_u64 v[40:41], v[164:165], 2, s[0:1]
	global_load_dword v40, v[40:41], off
	s_movk_i32 s0, 0x100
	s_waitcnt vmcnt(29)
	v_cmp_gt_i32_e64 s[4:5], 0, v45
	s_mov_b32 s22, 0
	s_waitcnt vmcnt(0)
; DI void topk_select(const float* scores, int* sel, char* smem) {
;     ...
; #pragma unroll
;     for (int j = 0; j < 33; ++j) {
;       const int idx = lane + 64 * j;
;       const unsigned bits = u[j];
;       u[j] = idx < nvis ? ((bits & 0x80000000u) ? ~bits : (bits | 0x80000000u)) : 0u;
;     }
	v_not_b32_e32 v41, v40
	v_cmp_gt_i32_e32 vcc, 0, v40
	s_nop 1
	v_cndmask_b32_e64 v66, -|v40|, v41, vcc
	v_not_b32_e32 v40, v42
	v_cmp_gt_i32_e32 vcc, 0, v42
	s_nop 1
	v_cndmask_b32_e64 v68, -|v42|, v40, vcc
	v_not_b32_e32 v40, v43
	v_cmp_gt_i32_e32 vcc, 0, v43
	s_nop 1
	v_cndmask_b32_e64 v67, -|v43|, v40, vcc
	v_not_b32_e32 v40, v44
	v_cmp_gt_i32_e32 vcc, 0, v44
	s_nop 1
	v_cndmask_b32_e64 v65, -|v44|, v40, vcc
	v_not_b32_e32 v40, v45
	v_cmp_lt_u32_e32 vcc, s0, v69
	v_cndmask_b32_e64 v40, -|v45|, v40, s[4:5]
	s_movk_i32 s0, 0x140
	v_cndmask_b32_e32 v64, 0, v40, vcc
	v_not_b32_e32 v40, v46
	v_cmp_gt_i32_e64 s[4:5], 0, v46
	v_cmp_lt_u32_e32 vcc, s0, v69
	s_movk_i32 s0, 0x180
	v_cndmask_b32_e64 v40, -|v46|, v40, s[4:5]
	v_cndmask_b32_e32 v63, 0, v40, vcc
	v_not_b32_e32 v40, v47
	v_cmp_gt_i32_e64 s[4:5], 0, v47
	v_cmp_lt_u32_e32 vcc, s0, v69
	s_movk_i32 s0, 0x1c0
	v_cndmask_b32_e64 v40, -|v47|, v40, s[4:5]
	v_cndmask_b32_e32 v62, 0, v40, vcc
	v_not_b32_e32 v40, v48
	v_cmp_gt_i32_e64 s[4:5], 0, v48
	v_cmp_lt_u32_e32 vcc, s0, v69
	s_movk_i32 s0, 0x200
	v_cndmask_b32_e64 v40, -|v48|, v40, s[4:5]
	v_cndmask_b32_e32 v61, 0, v40, vcc
	v_not_b32_e32 v40, v49
	v_cmp_gt_i32_e64 s[4:5], 0, v49
	v_cmp_lt_u32_e32 vcc, s0, v69
	s_movk_i32 s0, 0x240
	v_cndmask_b32_e64 v40, -|v49|, v40, s[4:5]
	v_cndmask_b32_e32 v60, 0, v40, vcc
	v_not_b32_e32 v40, v50
	v_cmp_gt_i32_e64 s[4:5], 0, v50
	v_cmp_lt_u32_e32 vcc, s0, v69
	s_movk_i32 s0, 0x280
	v_cndmask_b32_e64 v40, -|v50|, v40, s[4:5]
	v_cndmask_b32_e32 v59, 0, v40, vcc
	v_not_b32_e32 v40, v51
	v_cmp_gt_i32_e64 s[4:5], 0, v51
	v_cmp_lt_u32_e32 vcc, s0, v69
	s_movk_i32 s0, 0x2c0
	v_cndmask_b32_e64 v40, -|v51|, v40, s[4:5]
	v_cndmask_b32_e32 v58, 0, v40, vcc
	v_not_b32_e32 v40, v52
	v_cmp_gt_i32_e64 s[4:5], 0, v52
	v_cmp_lt_u32_e32 vcc, s0, v69
	s_movk_i32 s0, 0x300
	v_cndmask_b32_e64 v40, -|v52|, v40, s[4:5]
	v_cndmask_b32_e32 v57, 0, v40, vcc
	v_not_b32_e32 v40, v53
	v_cmp_gt_i32_e64 s[4:5], 0, v53
	v_cmp_lt_u32_e32 vcc, s0, v69
	s_movk_i32 s0, 0x340
	v_cndmask_b32_e64 v40, -|v53|, v40, s[4:5]
	v_cndmask_b32_e32 v56, 0, v40, vcc
	v_not_b32_e32 v40, v54
	v_cmp_gt_i32_e64 s[4:5], 0, v54
	v_cmp_lt_u32_e32 vcc, s0, v69
	s_movk_i32 s0, 0x380
	v_cndmask_b32_e64 v40, -|v54|, v40, s[4:5]
	v_cndmask_b32_e32 v55, 0, v40, vcc
	v_not_b32_e32 v40, v70
	v_cmp_gt_i32_e64 s[4:5], 0, v70
	v_cmp_lt_u32_e32 vcc, s0, v69
	s_movk_i32 s0, 0x3c0
	v_cndmask_b32_e64 v40, -|v70|, v40, s[4:5]
	v_cndmask_b32_e32 v54, 0, v40, vcc
	v_not_b32_e32 v40, v71
	v_cmp_gt_i32_e64 s[4:5], 0, v71
	v_cmp_lt_u32_e32 vcc, s0, v69
	s_movk_i32 s0, 0x400
	v_cndmask_b32_e64 v40, -|v71|, v40, s[4:5]
	v_cndmask_b32_e32 v53, 0, v40, vcc
	v_not_b32_e32 v40, v72
	v_cmp_gt_i32_e64 s[4:5], 0, v72
	v_cmp_lt_u32_e32 vcc, s0, v69
	s_movk_i32 s0, 0x440
	v_cndmask_b32_e64 v40, -|v72|, v40, s[4:5]
	v_cndmask_b32_e32 v52, 0, v40, vcc
	v_not_b32_e32 v40, v73
	v_cmp_gt_i32_e64 s[4:5], 0, v73
	v_cmp_lt_u32_e32 vcc, s0, v69
	s_movk_i32 s0, 0x480
	v_cndmask_b32_e64 v40, -|v73|, v40, s[4:5]
	v_cndmask_b32_e32 v51, 0, v40, vcc
	v_not_b32_e32 v40, v74
	v_cmp_gt_i32_e64 s[4:5], 0, v74
	v_cmp_lt_u32_e32 vcc, s0, v69
	s_movk_i32 s0, 0x4c0
	v_cndmask_b32_e64 v40, -|v74|, v40, s[4:5]
	v_cndmask_b32_e32 v50, 0, v40, vcc
	v_not_b32_e32 v40, v75
	v_cmp_gt_i32_e64 s[4:5], 0, v75
	v_cmp_lt_u32_e32 vcc, s0, v69
	s_movk_i32 s0, 0x500
	v_cndmask_b32_e64 v40, -|v75|, v40, s[4:5]
	v_cndmask_b32_e32 v49, 0, v40, vcc
	v_not_b32_e32 v40, v76
	v_cmp_gt_i32_e64 s[4:5], 0, v76
	v_cmp_lt_u32_e32 vcc, s0, v69
	s_movk_i32 s0, 0x540
	v_cndmask_b32_e64 v40, -|v76|, v40, s[4:5]
	v_cndmask_b32_e32 v48, 0, v40, vcc
	v_not_b32_e32 v40, v77
	v_cmp_gt_i32_e64 s[4:5], 0, v77
	v_cmp_lt_u32_e32 vcc, s0, v69
	s_movk_i32 s0, 0x580
	v_cndmask_b32_e64 v40, -|v77|, v40, s[4:5]
	v_cndmask_b32_e32 v47, 0, v40, vcc
	v_not_b32_e32 v40, v78
	v_cmp_gt_i32_e64 s[4:5], 0, v78
	v_cmp_lt_u32_e32 vcc, s0, v69
	s_movk_i32 s0, 0x5c0
	v_cndmask_b32_e64 v40, -|v78|, v40, s[4:5]
	v_cndmask_b32_e32 v46, 0, v40, vcc
	v_not_b32_e32 v40, v79
	v_cmp_gt_i32_e64 s[4:5], 0, v79
	v_cmp_lt_u32_e32 vcc, s0, v69
	s_movk_i32 s0, 0x600
	v_cndmask_b32_e64 v40, -|v79|, v40, s[4:5]
	v_cndmask_b32_e32 v45, 0, v40, vcc
	v_not_b32_e32 v40, v80
	v_cmp_gt_i32_e64 s[4:5], 0, v80
	v_cmp_lt_u32_e32 vcc, s0, v69
	s_movk_i32 s0, 0x640
	v_cndmask_b32_e64 v40, -|v80|, v40, s[4:5]
	v_cndmask_b32_e32 v44, 0, v40, vcc
	v_not_b32_e32 v40, v81
	v_cmp_gt_i32_e64 s[4:5], 0, v81
	v_cmp_lt_u32_e32 vcc, s0, v69
	s_movk_i32 s0, 0x680
	v_cndmask_b32_e64 v40, -|v81|, v40, s[4:5]
	v_cndmask_b32_e32 v43, 0, v40, vcc
	v_not_b32_e32 v40, v82
	v_cmp_gt_i32_e64 s[4:5], 0, v82
	v_cmp_lt_u32_e32 vcc, s0, v69
	s_movk_i32 s0, 0x6c0
	v_cndmask_b32_e64 v40, -|v82|, v40, s[4:5]
	v_cndmask_b32_e32 v42, 0, v40, vcc
	v_not_b32_e32 v40, v83
	v_cmp_gt_i32_e64 s[4:5], 0, v83
	v_cmp_lt_u32_e32 vcc, s0, v69
	s_movk_i32 s0, 0x700
	v_cndmask_b32_e64 v40, -|v83|, v40, s[4:5]
	v_cndmask_b32_e32 v41, 0, v40, vcc
	v_not_b32_e32 v40, v84
	v_cmp_gt_i32_e64 s[4:5], 0, v84
	v_cmp_lt_u32_e32 vcc, s0, v69
	s_movk_i32 s0, 0x740
	v_cndmask_b32_e64 v40, -|v84|, v40, s[4:5]
	v_not_b32_e32 v70, v39
	v_cmp_gt_i32_e64 s[4:5], 0, v39
	v_cndmask_b32_e32 v40, 0, v40, vcc
	v_cmp_lt_u32_e32 vcc, s0, v69
	v_cndmask_b32_e64 v39, -|v39|, v70, s[4:5]
	s_movk_i32 s0, 0x780
	v_not_b32_e32 v70, v38
	v_cmp_gt_i32_e64 s[4:5], 0, v38
	v_cndmask_b32_e32 v39, 0, v39, vcc
	v_cmp_lt_u32_e32 vcc, s0, v69
	v_cndmask_b32_e64 v38, -|v38|, v70, s[4:5]
	s_movk_i32 s0, 0x7c0
	v_not_b32_e32 v70, v37
	v_cmp_gt_i32_e64 s[4:5], 0, v37
	v_cndmask_b32_e32 v38, 0, v38, vcc
	v_cmp_lt_u32_e32 vcc, s0, v69
	v_cndmask_b32_e64 v37, -|v37|, v70, s[4:5]
	s_movk_i32 s0, 0x800
	v_cndmask_b32_e32 v37, 0, v37, vcc
	v_cmp_lt_u32_e32 vcc, s0, v69
	v_not_b32_e32 v69, v36
	v_cmp_gt_i32_e64 s[4:5], 0, v36
	s_mov_b32 s0, 32
	s_nop 0
	v_cndmask_b32_e64 v36, -|v36|, v69, s[4:5]
	v_cndmask_b32_e32 v36, 0, v36, vcc
; DI void topk_select(const float* scores, int* sel, char* smem) {
;     ...
;       const unsigned cand = prefix | (1u << bit);
;       int cnt = 0;
; #pragma unroll
;       for (int j = 0; j < 33; ++j) cnt += __builtin_popcountll(__ballot(u[j] >= cand));
;       if (cnt >= 256) prefix = cand;
;     }
;     {
;       const unsigned hi = prefix >> 20;
;       const unsigned long long lm = (1ull << lane) - 1ull;
;       int above = 0, nb = 0;
; #pragma unroll
;       for (int j = 0; j < 33; ++j) {
;         above += __builtin_popcountll(__ballot((u[j] >> 20) > hi));
;         const bool pb = (u[j] >> 20) == hi;
;         const unsigned long long mb_ = __ballot(pb);
;         const int pos = nb + __builtin_popcountll(mb_ & lm);
;         if (pb && pos < 64) wsc[pos] = u[j];
.LBB0_583:
	s_add_i32 s0, s0, -1
	s_lshl_b32 s1, 1, s0
	s_or_b32 s1, s1, s22
	v_cmp_le_u32_e32 vcc, s1, v66
	s_bcnt1_i32_b64 s4, vcc
	v_cmp_le_u32_e32 vcc, s1, v68
	s_bcnt1_i32_b64 s5, vcc
	v_cmp_le_u32_e32 vcc, s1, v67
	s_add_i32 s4, s5, s4
	s_bcnt1_i32_b64 s5, vcc
	v_cmp_le_u32_e32 vcc, s1, v65
	s_add_i32 s4, s4, s5
	s_bcnt1_i32_b64 s5, vcc
	v_cmp_le_u32_e32 vcc, s1, v64
	s_add_i32 s4, s4, s5
	s_bcnt1_i32_b64 s5, vcc
	v_cmp_le_u32_e32 vcc, s1, v63
	s_add_i32 s4, s4, s5
	s_bcnt1_i32_b64 s5, vcc
	v_cmp_le_u32_e32 vcc, s1, v62
	s_add_i32 s4, s4, s5
	s_bcnt1_i32_b64 s5, vcc
	v_cmp_le_u32_e32 vcc, s1, v61
	s_add_i32 s4, s4, s5
	s_bcnt1_i32_b64 s5, vcc
	s_cmp_le_u32 s100, 8
	s_cbranch_scc1 .Ltopk_radix_fin
	v_cmp_le_u32_e32 vcc, s1, v60
	s_add_i32 s4, s4, s5
	s_bcnt1_i32_b64 s5, vcc
	v_cmp_le_u32_e32 vcc, s1, v59
	s_add_i32 s4, s4, s5
	s_bcnt1_i32_b64 s5, vcc
	v_cmp_le_u32_e32 vcc, s1, v58
	s_add_i32 s4, s4, s5
	s_bcnt1_i32_b64 s5, vcc
	v_cmp_le_u32_e32 vcc, s1, v57
	s_add_i32 s4, s4, s5
	s_bcnt1_i32_b64 s5, vcc
	s_cmp_le_u32 s100, 12
	s_cbranch_scc1 .Ltopk_radix_fin
	v_cmp_le_u32_e32 vcc, s1, v56
	s_add_i32 s4, s4, s5
	s_bcnt1_i32_b64 s5, vcc
	v_cmp_le_u32_e32 vcc, s1, v55
	s_add_i32 s4, s4, s5
	s_bcnt1_i32_b64 s5, vcc
	v_cmp_le_u32_e32 vcc, s1, v54
	s_add_i32 s4, s4, s5
	s_bcnt1_i32_b64 s5, vcc
	v_cmp_le_u32_e32 vcc, s1, v53
	s_add_i32 s4, s4, s5
	s_bcnt1_i32_b64 s5, vcc
	s_cmp_le_u32 s100, 16
	s_cbranch_scc1 .Ltopk_radix_fin
	v_cmp_le_u32_e32 vcc, s1, v52
	s_add_i32 s4, s4, s5
	s_bcnt1_i32_b64 s5, vcc
	v_cmp_le_u32_e32 vcc, s1, v51
	s_add_i32 s4, s4, s5
	s_bcnt1_i32_b64 s5, vcc
	v_cmp_le_u32_e32 vcc, s1, v50
	s_add_i32 s4, s4, s5
	s_bcnt1_i32_b64 s5, vcc
	v_cmp_le_u32_e32 vcc, s1, v49
	s_add_i32 s4, s4, s5
	s_bcnt1_i32_b64 s5, vcc
	s_cmp_le_u32 s100, 20
	s_cbranch_scc1 .Ltopk_radix_fin
	v_cmp_le_u32_e32 vcc, s1, v48
	s_add_i32 s4, s4, s5
	s_bcnt1_i32_b64 s5, vcc
	v_cmp_le_u32_e32 vcc, s1, v47
	s_add_i32 s4, s4, s5
	s_bcnt1_i32_b64 s5, vcc
	v_cmp_le_u32_e32 vcc, s1, v46
	s_add_i32 s4, s4, s5
	s_bcnt1_i32_b64 s5, vcc
	v_cmp_le_u32_e32 vcc, s1, v45
	s_add_i32 s4, s4, s5
	s_bcnt1_i32_b64 s5, vcc
	s_cmp_le_u32 s100, 24
	s_cbranch_scc1 .Ltopk_radix_fin
	v_cmp_le_u32_e32 vcc, s1, v44
	s_add_i32 s4, s4, s5
	s_bcnt1_i32_b64 s5, vcc
	v_cmp_le_u32_e32 vcc, s1, v43
	s_add_i32 s4, s4, s5
	s_bcnt1_i32_b64 s5, vcc
	v_cmp_le_u32_e32 vcc, s1, v42
	s_add_i32 s4, s4, s5
	s_bcnt1_i32_b64 s5, vcc
	v_cmp_le_u32_e32 vcc, s1, v41
	s_add_i32 s4, s4, s5
	s_bcnt1_i32_b64 s5, vcc
	s_cmp_le_u32 s100, 28
	s_cbranch_scc1 .Ltopk_radix_fin
	v_cmp_le_u32_e32 vcc, s1, v40
	s_add_i32 s4, s4, s5
	s_bcnt1_i32_b64 s5, vcc
	v_cmp_le_u32_e32 vcc, s1, v39
	s_add_i32 s4, s4, s5
	s_bcnt1_i32_b64 s5, vcc
	v_cmp_le_u32_e32 vcc, s1, v38
	s_add_i32 s4, s4, s5
	s_bcnt1_i32_b64 s5, vcc
	v_cmp_le_u32_e32 vcc, s1, v37
	s_add_i32 s4, s4, s5
	s_bcnt1_i32_b64 s5, vcc
	v_cmp_le_u32_e32 vcc, s1, v36
	s_add_i32 s4, s4, s5
	s_bcnt1_i32_b64 s5, vcc
.Ltopk_radix_fin:
	s_add_i32 s4, s4, s5
	s_cmpk_gt_u32 s4, 0xff
	s_cselect_b32 s22, s1, s22
	s_cmp_lt_u32 s0, 21
	s_cbranch_scc0 .LBB0_583
	s_lshr_b32 s20, s22, 20
	v_lshrrev_b32_e32 v69, 20, v66
	v_cmp_lt_u32_e64 s[40:41], s20, v69
	v_cmp_eq_u32_e32 vcc, s20, v69
	s_and_saveexec_b64 s[0:1], vcc
	s_cbranch_execz .LBB0_586
	v_and_b32_e32 v70, vcc_lo, v0
	v_and_b32_e32 v69, vcc_hi, v1
	v_bcnt_u32_b32 v70, v70, 0
	v_bcnt_u32_b32 v69, v69, v70
	v_lshl_add_u32 v69, v69, 2, s2
	ds_write_b32 v69, v66

; __global__ void __launch_bounds__(NT, 2) mega(Params p) {
;   cg::grid_group grid = cg::this_grid();
;   __shared__ __attribute__((aligned(16))) char smem[SMEM_BYTES];
	.amdhsa_kernel _Z4mega6Params
		.amdhsa_group_segment_fixed_size 148496
		.amdhsa_private_segment_fixed_size 0
		.amdhsa_kernarg_size 456
		.amdhsa_user_sgpr_count 2
		.amdhsa_user_sgpr_dispatch_ptr 0
		.amdhsa_user_sgpr_queue_ptr 0
		.amdhsa_user_sgpr_kernarg_segment_ptr 1
		.amdhsa_user_sgpr_dispatch_id 0
		.amdhsa_user_sgpr_kernarg_preload_length 0
		.amdhsa_user_sgpr_kernarg_preload_offset 0
		.amdhsa_user_sgpr_private_segment_size 0
		.amdhsa_uses_dynamic_stack 0
		.amdhsa_enable_private_segment 0
		.amdhsa_system_sgpr_workgroup_id_x 1
		.amdhsa_system_sgpr_workgroup_id_y 0
		.amdhsa_system_sgpr_workgroup_id_z 0
		.amdhsa_system_sgpr_workgroup_info 0
		.amdhsa_system_vgpr_workitem_id 2
		.amdhsa_next_free_vgpr 256
		.amdhsa_next_free_sgpr 101
		.amdhsa_accum_offset 256
		.amdhsa_reserve_vcc 1
		.amdhsa_float_round_mode_32 0
		.amdhsa_float_round_mode_16_64 0
		.amdhsa_float_denorm_mode_32 3
		.amdhsa_float_denorm_mode_16_64 3
		.amdhsa_dx10_clamp 1
		.amdhsa_ieee_mode 1
		.amdhsa_fp16_overflow 0
		.amdhsa_tg_split 0
		.amdhsa_exception_fp_ieee_invalid_op 0
		.amdhsa_exception_fp_denorm_src 0
		.amdhsa_exception_fp_ieee_div_zero 0
		.amdhsa_exception_fp_ieee_overflow 0
		.amdhsa_exception_fp_ieee_underflow 0
		.amdhsa_exception_fp_ieee_inexact 0
		.amdhsa_exception_int_div_zero 0
	.end_amdhsa_kernel

; __global__ void __launch_bounds__(NT, 2) mega(Params p) {
;   cg::grid_group grid = cg::this_grid();
;   __shared__ __attribute__((aligned(16))) char smem[SMEM_BYTES];
amdhsa.kernels:
  - .agpr_count:     0
    .args:
      - .offset:         0
        .size:           200
        .value_kind:     by_value
      - .offset:         200
        .size:           4
        .value_kind:     hidden_block_count_x
      - .offset:         204
        .size:           4
        .value_kind:     hidden_block_count_y
      - .offset:         208
        .size:           4
        .value_kind:     hidden_block_count_z
      - .offset:         212
        .size:           2
        .value_kind:     hidden_group_size_x
      - .offset:         214
        .size:           2
        .value_kind:     hidden_group_size_y
      - .offset:         216
        .size:           2
        .value_kind:     hidden_group_size_z
      - .offset:         218
        .size:           2
        .value_kind:     hidden_remainder_x
      - .offset:         220
        .size:           2
        .value_kind:     hidden_remainder_y
      - .offset:         222
        .size:           2
        .value_kind:     hidden_remainder_z
      - .offset:         240
        .size:           8
        .value_kind:     hidden_global_offset_x
      - .offset:         248
        .size:           8
        .value_kind:     hidden_global_offset_y
      - .offset:         256
        .size:           8
        .value_kind:     hidden_global_offset_z
      - .offset:         264
        .size:           2
        .value_kind:     hidden_grid_dims
      - .offset:         288
        .size:           8
        .value_kind:     hidden_multigrid_sync_arg
    .group_segment_fixed_size: 148496
    .kernarg_segment_align: 8
    .kernarg_segment_size: 456
    .language:       OpenCL C
    .language_version:
      - 2
      - 0
    .max_flat_workgroup_size: 512
    .name:           _Z4mega6Params
    .private_segment_fixed_size: 0
    .sgpr_count:     107
    .sgpr_spill_count: 268
    .symbol:         _Z4mega6Params.kd
    .uniform_work_group_size: 1
    .uses_dynamic_stack: false
    .vgpr_count:     256
    .vgpr_spill_count: 0
    .wavefront_size: 64
